# static priority raise for waves 0-3 in GEMM streams with reset to 0 at non-GEMM phase entries
# baseline (speedup 1.0000x reference)
.LBB0_379:
	s_setprio 0
	s_cmp_lt_i32 s4, 3
	s_cselect_b64 s[0:1], -1, 0
	s_cmp_gt_i32 s5, 2
	s_cselect_b64 s[2:3], -1, 0
	s_and_b64 s[0:1], s[0:1], s[2:3]
	s_andn2_b64 vcc, exec, s[0:1]
	s_cbranch_vccnz .LBB0_439
	v_readlane_b32 s0, v254, 15
	s_lshl_b32 s0, s0, 3
	s_add_i32 s2, s76, s0
	s_cmpk_gt_i32 s2, 0x1fff
	v_readlane_b32 s1, v254, 16
	v_mbcnt_lo_u32_b32 v0, -1, 0
	v_mbcnt_hi_u32_b32 v0, -1, v0
	s_cbranch_scc1 .LBB0_383
	v_ashrrev_i32_e32 v4, 3, v0
	v_lshlrev_b32_e32 v0, 3, v0
	v_and_b32_e32 v5, 56, v0
	v_readlane_b32 s0, v254, 6
	v_lshlrev_b32_e32 v2, 1, v5
	v_mov_b32_e32 v3, 0
	s_mov_b32 s6, s0
	s_lshl_b32 s3, s0, 3
	s_lshl_b32 s0, s76, 14
	v_lshl_add_u64 v[6:7], s[58:59], 0, v[2:3]
	s_mov_b64 s[4:5], 0x44000000
	s_add_i32 s0, s0, 0
	v_lshl_add_u64 v[0:1], v[6:7], 0, s[4:5]
	s_mov_b64 s[4:5], 0x48000000
	v_add_u32_e32 v14, s0, v2
	v_lshl_add_u64 v[2:3], v[6:7], 0, s[4:5]
	s_movk_i32 s4, 0x84
	v_lshlrev_b32_e32 v7, 1, v4
	v_mul_u32_u24_e32 v8, 0x84, v5
	v_mul_lo_u32 v15, v4, s4
	v_readlane_b32 s4, v254, 15
	v_readlane_b32 s1, v254, 7
	v_add3_u32 v7, s0, v7, v8
	s_lshl_b32 s0, s4, 4
	s_lshl_b32 s4, s76, 1
	v_add_u32_e32 v14, v14, v15
	s_mov_b32 s1, 0
	v_add_u32_e32 v6, 56, v4
	v_add_u32_e32 v8, 8, v4
	v_add_u32_e32 v9, 16, v4
	v_add_u32_e32 v10, 24, v4
	v_add_u32_e32 v11, 32, v4
	v_add_u32_e32 v12, 40, v4
	v_add_u32_e32 v13, 48, v4
	s_add_i32 s8, s0, s4
	s_lshl_b32 s9, s6, 4
	v_add_u32_e32 v15, 0x420, v14
	v_add_u32_e32 v16, 0x428, v14
	v_add_u32_e32 v17, 0x840, v14
	v_add_u32_e32 v18, 0x848, v14
	v_add_u32_e32 v19, 0xc60, v14
	v_add_u32_e32 v20, 0xc68, v14
	v_add_u32_e32 v21, 0x1080, v14
	v_add_u32_e32 v22, 0x1088, v14
	v_add_u32_e32 v23, 0x14a0, v14
	v_add_u32_e32 v24, 0x14a8, v14
	v_add_u32_e32 v25, 0x18c0, v14
	v_add_u32_e32 v26, 0x18c8, v14
	v_add_u32_e32 v27, 0x1ce0, v14
	v_add_u32_e32 v28, 0x1ce8, v14
	v_mov_b32_e32 v29, 0x7f
	v_readlane_b32 s5, v254, 16

.LBB0_478:
	s_setprio 0
	s_lshl_b32 s0, s76, 14
	s_add_i32 s2, s0, 0
	s_add_u32 s3, s58, 0x16e00000
	s_addc_u32 s10, s59, 0
	s_add_u32 s11, s58, 0x14e00000
	s_addc_u32 s12, s59, 0
	s_add_u32 s13, s58, 0xf800000
	s_addc_u32 s14, s59, 0
	s_add_u32 s15, s58, 0x4c00000
	s_addc_u32 s16, s59, 0
	s_add_u32 s17, s58, 0x2c00000
	s_addc_u32 s18, s59, 0
	s_add_u32 s19, s58, 0xc00000
	s_addc_u32 s20, s59, 0
	s_add_u32 s21, s58, 0x400000
	s_mov_b32 s6, 0
	s_addc_u32 s22, s59, 0
	v_mov_b32_e32 v1, 0
	s_mov_b32 s23, 0x20000
	s_mov_b32 s24, 0x40000
	s_mov_b32 s25, 0x60000
	s_mov_b32 s26, 0x80000
	s_mov_b32 s27, 0xa0000
	s_mov_b32 s28, 0xc0000
	s_mov_b32 s29, 0xe0000
	s_movk_i32 s30, 0x84
	s_movk_i32 s31, 0x5600
	s_mov_b32 s33, 0xac00
	s_mov_b32 s7, 0
	s_branch .LBB0_481

.LBB0_592:
	s_setprio 0
	s_cmp_lt_i32 s4, 5
	s_cselect_b64 s[0:1], -1, 0
	s_cmp_gt_i32 s5, 4
	s_cselect_b64 s[2:3], -1, 0
	s_and_b64 s[0:1], s[0:1], s[2:3]
	s_andn2_b64 vcc, exec, s[0:1]
	s_cbranch_vccnz .LBB0_672
	v_readlane_b32 s0, v254, 15
	s_cmpk_gt_i32 s0, 0x3ff
	v_readlane_b32 s1, v254, 16
	s_cbranch_scc1 .LBB0_613
	v_readlane_b32 s12, v254, 33
	v_readlane_b32 s14, v254, 35
	v_readlane_b32 s15, v254, 36
	s_add_u32 s3, s14, 2.0
	s_addc_u32 s27, s15, 0
	s_add_u32 s30, s14, 0x44000000
	s_addc_u32 s31, s15, 0
	s_lshl_b32 s2, s76, 3
	s_or_b32 s0, s2, 1
	s_lshl_b32 s35, s0, 1
	s_lshl_b32 s5, s0, 10
	s_or_b32 s0, s2, 2
	s_lshl_b32 s36, s0, 1
	s_lshl_b32 s6, s0, 10
	s_or_b32 s0, s2, 3
	s_lshl_b32 s37, s0, 1
	s_lshl_b32 s7, s0, 10
	s_or_b32 s0, s2, 4
	s_lshl_b32 s38, s0, 1
	s_lshl_b32 s8, s0, 10
	s_or_b32 s0, s2, 5
	s_lshl_b32 s39, s0, 1
	s_lshl_b32 s9, s0, 10
	s_or_b32 s0, s2, 6
	s_lshl_b32 s40, s0, 1
	s_lshl_b32 s10, s0, 10
	s_or_b32 s0, s2, 7
	s_lshl_b32 s34, s76, 4
	s_lshl_b32 s4, s76, 13
	s_lshl_b32 s41, s0, 1
	s_lshl_b32 s11, s0, 10
	v_readlane_b32 s12, v254, 0
	s_cmpk_lt_u32 s12, 0x280
	s_cselect_b64 s[16:17], -1, 0
	s_lshl_b32 s0, s76, 1
	s_mov_b32 s1, 0
	s_lshl_b64 s[0:1], s[0:1], 14
	s_add_u32 s0, s14, s0
	s_addc_u32 s1, s15, s1
	s_add_u32 s42, s0, 0x17800000
	s_addc_u32 s43, s1, 0
	s_add_u32 s18, s14, 0x4c000000
	s_addc_u32 s19, s15, 0
	s_and_b32 s20, s12, 0xffffffc0
	v_readlane_b32 s48, v254, 17
	s_ashr_i32 s21, s20, 31
	v_readlane_b32 s58, v254, 27
	v_readlane_b32 s59, v254, 28
	s_add_i32 s44, s2, 0
	s_lshl_b64 s[0:1], s[20:21], 2
	s_mov_b64 s[46:47], s[58:59]
	s_add_u32 s45, s46, s0
	s_mul_i32 s0, s76, 0x21f8
	s_addc_u32 s46, s47, s1
	s_add_i32 s47, s44, s0
	s_add_u32 s22, s14, 0x54000000
	s_addc_u32 s23, s15, 0
	s_add_u32 s24, s14, 0x30000000
	v_readlane_b32 s49, v254, 18
	v_readlane_b32 s50, v254, 19
	v_readlane_b32 s51, v254, 20
	v_readlane_b32 s52, v254, 21
	v_readlane_b32 s53, v254, 22
	v_readlane_b32 s54, v254, 23
	v_readlane_b32 s55, v254, 24
	v_readlane_b32 s56, v254, 25
	v_readlane_b32 s57, v254, 26
	s_addc_u32 s25, s15, 0
	s_lshl_b32 s0, s76, 11
	v_readlane_b32 s60, v254, 29
	v_readlane_b32 s61, v254, 30
	v_readlane_b32 s62, v254, 31
	v_readlane_b32 s63, v254, 32
	s_add_i32 s49, s0, 0
	s_add_i32 s50, s4, 0
	s_add_i32 s51, s5, 0
	s_add_i32 s52, s6, 0
	s_add_i32 s53, s7, 0
	s_add_i32 s54, s8, 0
	s_add_i32 s55, s9, 0
	s_add_i32 s56, s10, 0
	s_add_i32 s57, s11, 0
	v_mbcnt_lo_u32_b32 v0, -1, 0
	v_readlane_b32 s0, v254, 15
	s_add_i32 s48, s76, -3
	v_mov_b32_e32 v129, 0
	s_add_i32 s50, s50, 0x8000
	s_add_i32 s51, s51, 0x8000
	s_add_i32 s52, s52, 0x8000
	s_add_i32 s53, s53, 0x8000
	s_add_i32 s54, s54, 0x8000
	s_add_i32 s55, s55, 0x8000
	s_add_i32 s56, s56, 0x8000
	s_add_i32 s57, s57, 0x8000
	s_mov_b32 s58, 0x5040100
	s_movk_i32 s59, 0x1000
	s_movk_i32 s60, 0x5000
	s_movk_i32 s61, 0x2000
	s_movk_i32 s62, 0x6000
	s_movk_i32 s63, 0x3000
	s_movk_i32 s64, 0x7000
	s_mov_b32 s65, 0x100000
	s_movk_i32 s66, 0x110
	s_mov_b32 s26, 0x3b000000
	s_mov_b32 s67, 0xf800000
	v_mov_b32_e32 v136, 0x260
	s_mov_b32 s73, 0x10000
	s_mov_b32 s78, 0x20000
	s_mov_b32 s79, 0x30000
	v_mbcnt_hi_u32_b32 v137, -1, v0
	s_mov_b32 s82, s0
	v_readlane_b32 s13, v254, 34
	v_readlane_b32 s1, v254, 16
	s_branch .LBB0_596

.LBB0_848:
	s_setprio 0
	s_cmp_lt_i32 s4, 8
	s_cselect_b64 s[0:1], -1, 0
	s_cmp_gt_i32 s5, 7
	s_cselect_b64 s[2:3], -1, 0
	s_and_b64 s[0:1], s[0:1], s[2:3]
	s_andn2_b64 vcc, exec, s[0:1]
	s_cbranch_vccnz .LBB0_912
	v_readlane_b32 s0, v254, 15
	s_lshl_b32 s0, s0, 3
	s_add_i32 s6, s76, s0
	s_cmp_gt_i32 s6, 63
	v_readlane_b32 s1, v254, 16
	v_mbcnt_lo_u32_b32 v130, -1, 0
	v_mbcnt_hi_u32_b32 v130, -1, v130
	s_cbranch_scc1 .LBB0_851
	v_lshl_add_u32 v0, s6, 6, v130
	v_ashrrev_i32_e32 v1, 31, v0
	v_readlane_b32 s8, v254, 17
	v_lshlrev_b64 v[2:3], 2, v[0:1]
	v_readlane_b32 s9, v254, 18
	v_readlane_b32 s10, v254, 19
	v_readlane_b32 s11, v254, 20
	v_readlane_b32 s12, v254, 21
	v_readlane_b32 s13, v254, 22
	v_readlane_b32 s14, v254, 23
	v_readlane_b32 s15, v254, 24
	v_readlane_b32 s16, v254, 25
	v_readlane_b32 s17, v254, 26
	v_readlane_b32 s18, v254, 27
	v_readlane_b32 s19, v254, 28
	v_readlane_b32 s20, v254, 29
	v_readlane_b32 s21, v254, 30
	v_readlane_b32 s22, v254, 31
	v_readlane_b32 s23, v254, 32
	v_lshl_add_u64 v[0:1], v[0:1], 3, s[58:59]
	s_mov_b32 s0, 0x3f9837f0
	v_lshl_add_u64 v[4:5], s[22:23], 0, v[2:3]
	v_readlane_b32 s8, v254, 37
	v_readlane_b32 s9, v254, 38
	global_load_dword v4, v[4:5], off
	v_add_co_u32_e32 v0, vcc, 0x48020000, v0
	v_lshl_add_u64 v[2:3], s[8:9], 0, v[2:3]
	global_load_dword v5, v[2:3], off
	v_addc_co_u32_e32 v1, vcc, 0, v1, vcc
	v_readlane_b32 s10, v254, 39
	v_readlane_b32 s11, v254, 40
	v_readlane_b32 s12, v254, 41
	v_readlane_b32 s13, v254, 42
	v_readlane_b32 s14, v254, 43
	v_readlane_b32 s15, v254, 44
	v_readlane_b32 s16, v254, 45
	v_readlane_b32 s17, v254, 46
	v_readlane_b32 s18, v254, 47
	v_readlane_b32 s19, v254, 48
	v_readlane_b32 s20, v254, 49
	v_readlane_b32 s21, v254, 50
	v_readlane_b32 s22, v254, 51
	v_readlane_b32 s23, v254, 52
	s_waitcnt vmcnt(0)
	v_pk_mul_f32 v[2:3], v[4:5], s[0:1] op_sel_hi:[1,0]
	global_store_dwordx2 v[0:1], v[2:3], off nt

.LBB0_1084:
	s_setprio 0
	s_cmp_lt_i32 s4, 11
	s_cselect_b64 s[0:1], -1, 0
	s_cmp_gt_i32 s5, 10
	s_cselect_b64 s[2:3], -1, 0
	s_and_b64 s[0:1], s[0:1], s[2:3]
	s_andn2_b64 vcc, exec, s[0:1]
	s_cbranch_vccnz .LBB0_1088
	v_readlane_b32 s0, v254, 15
	s_lshl_b32 s0, s0, 3
	s_add_i32 s2, s76, s0
	s_cmpk_gt_i32 s2, 0x3fff
	v_readlane_b32 s1, v254, 16
	v_mbcnt_lo_u32_b32 v64, -1, 0
	v_mbcnt_hi_u32_b32 v64, -1, v64
	s_cbranch_scc1 .LBB0_1088
	v_readlane_b32 s4, v254, 37
	v_ashrrev_i32_e32 v65, 31, v64
	v_readlane_b32 s12, v254, 45
	v_readlane_b32 s13, v254, 46
	v_readlane_b32 s14, v254, 47
	v_readlane_b32 s15, v254, 48
	v_readlane_b32 s16, v254, 49
	v_readlane_b32 s17, v254, 50
	v_lshlrev_b64 v[66:67], 4, v[64:65]
	v_readlane_b32 s18, v254, 51
	v_readlane_b32 s19, v254, 52
	s_mov_b64 s[12:13], s[16:17]
	v_lshl_add_u64 v[48:49], s[12:13], 0, v[66:67]
	v_add_co_u32_e32 v32, vcc, 0x1000, v48
	global_load_dwordx4 v[0:3], v[48:49], off
	global_load_dwordx4 v[4:7], v[48:49], off offset:1024
	global_load_dwordx4 v[8:11], v[48:49], off offset:2048
	global_load_dwordx4 v[12:15], v[48:49], off offset:3072
	v_addc_co_u32_e32 v33, vcc, 0, v49, vcc
	v_add_co_u32_e32 v50, vcc, 0x2000, v48
	global_load_dwordx4 v[16:19], v[32:33], off
	global_load_dwordx4 v[20:23], v[32:33], off offset:1024
	global_load_dwordx4 v[24:27], v[32:33], off offset:2048
	global_load_dwordx4 v[28:31], v[32:33], off offset:3072
	v_addc_co_u32_e32 v51, vcc, 0, v49, vcc
	v_add_co_u32_e32 v68, vcc, 0x3000, v48
	global_load_dwordx4 v[32:35], v[50:51], off
	global_load_dwordx4 v[36:39], v[50:51], off offset:1024
	global_load_dwordx4 v[40:43], v[50:51], off offset:2048
	global_load_dwordx4 v[44:47], v[50:51], off offset:3072
	v_addc_co_u32_e32 v69, vcc, 0, v49, vcc
	global_load_dwordx4 v[48:51], v[68:69], off
	global_load_dwordx4 v[52:55], v[68:69], off offset:1024
	global_load_dwordx4 v[56:59], v[68:69], off offset:2048
	global_load_dwordx4 v[60:63], v[68:69], off offset:3072
	v_mbcnt_lo_u32_b32 v68, -1, 0
	v_mbcnt_hi_u32_b32 v68, -1, v68
	v_and_b32_e32 v69, 64, v68
	v_add_u32_e32 v69, 64, v69
	v_xor_b32_e32 v70, 1, v68
	v_cmp_lt_i32_e32 vcc, v70, v69
	v_readlane_b32 s0, v254, 6
	s_mov_b64 s[14:15], s[18:19]
	v_cndmask_b32_e32 v70, v68, v70, vcc
	v_lshlrev_b32_e32 v168, 2, v70
	v_xor_b32_e32 v70, 2, v68
	v_cmp_lt_i32_e32 vcc, v70, v69
	v_readlane_b32 s1, v254, 7
	s_lshl_b32 s4, s0, 3
	v_cndmask_b32_e32 v70, v68, v70, vcc
	v_lshlrev_b32_e32 v169, 2, v70
	v_xor_b32_e32 v70, 4, v68
	v_cmp_lt_i32_e32 vcc, v70, v69
	s_mov_b64 s[0:1], 0x1000
	s_ashr_i32 s3, s2, 31
	v_cndmask_b32_e32 v70, v68, v70, vcc
	v_lshlrev_b32_e32 v170, 2, v70
	v_xor_b32_e32 v70, 8, v68
	v_cmp_lt_i32_e32 vcc, v70, v69
	v_readlane_b32 s5, v254, 38
	v_readlane_b32 s6, v254, 39
	v_cndmask_b32_e32 v70, v68, v70, vcc
	v_lshlrev_b32_e32 v171, 2, v70
	v_xor_b32_e32 v70, 16, v68
	v_cmp_lt_i32_e32 vcc, v70, v69
	v_readlane_b32 s7, v254, 40
	v_readlane_b32 s8, v254, 41
	v_cndmask_b32_e32 v70, v68, v70, vcc
	v_lshlrev_b32_e32 v172, 2, v70
	v_xor_b32_e32 v70, 32, v68
	v_cmp_lt_i32_e32 vcc, v70, v69
	v_readlane_b32 s9, v254, 42
	v_readlane_b32 s10, v254, 43
	v_cndmask_b32_e32 v68, v68, v70, vcc
	v_lshlrev_b32_e32 v173, 2, v68
	v_lshl_add_u64 v[68:69], s[14:15], 0, v[66:67]
	v_lshl_add_u64 v[70:71], v[68:69], 0, s[0:1]
	s_mov_b64 s[0:1], 0x1400
	v_lshl_add_u64 v[72:73], v[68:69], 0, s[0:1]
	s_mov_b64 s[0:1], 0x1800
	v_lshl_add_u64 v[74:75], v[68:69], 0, s[0:1]
	s_mov_b64 s[0:1], 0x1c00
	v_lshl_add_u64 v[76:77], v[68:69], 0, s[0:1]
	s_mov_b64 s[0:1], 0x2000
	v_lshl_add_u64 v[78:79], v[68:69], 0, s[0:1]
	s_mov_b64 s[0:1], 0x2400
	v_lshl_add_u64 v[80:81], v[68:69], 0, s[0:1]
	s_mov_b64 s[0:1], 0x2800
	v_lshl_add_u64 v[82:83], v[68:69], 0, s[0:1]
	s_mov_b64 s[0:1], 0x2c00
	v_lshl_add_u64 v[84:85], v[68:69], 0, s[0:1]
	s_mov_b64 s[0:1], 0x3000
	v_lshl_add_u64 v[86:87], v[68:69], 0, s[0:1]
	s_mov_b64 s[0:1], 0x3400
	v_lshl_add_u64 v[88:89], v[68:69], 0, s[0:1]
	s_mov_b64 s[0:1], 0x3800
	v_lshl_add_u64 v[90:91], v[68:69], 0, s[0:1]
	s_mov_b64 s[0:1], 0x3c00
	v_lshl_add_u64 v[92:93], v[68:69], 0, s[0:1]
	s_lshl_b64 s[0:1], s[2:3], 14
	s_add_u32 s0, s56, s0
	s_addc_u32 s1, s57, s1
	s_ashr_i32 s5, s4, 31
	v_lshl_add_u64 v[94:95], s[0:1], 0, v[66:67]
	s_lshl_b64 s[6:7], s[4:5], 14
	s_lshl_b64 s[0:1], s[2:3], 13
	s_add_u32 s0, s58, s0
	s_addc_u32 s1, s59, s1
	v_readlane_b32 s11, v254, 44
	v_lshl_add_u64 v[64:65], v[64:65], 3, s[0:1]
	s_mov_b64 s[0:1], 0x38000000
	s_movk_i32 s10, 0x1000
	s_movk_i32 s11, 0x2000
	s_movk_i32 s12, 0x3000
	v_lshl_add_u64 v[96:97], v[64:65], 0, s[0:1]
	s_lshl_b64 s[8:9], s[4:5], 13
	v_mov_b32_e32 v174, 0x3727c5ac
	s_mov_b32 s3, 0xf800000
	v_mov_b32_e32 v175, 0x260
	v_mbcnt_lo_u32_b32 v228, -1, 0
	v_mbcnt_hi_u32_b32 v228, -1, v228
	v_lshlrev_b32_e32 v232, 4, v228
	s_lshl_b32 s98, s76, 10
	v_add_u32_e32 v229, s98, v232
	v_add_u32_e32 v230, 0x2000, v229
	global_load_dwordx4 v[236:239], v229, s[14:15]
	global_load_dwordx4 v[240:243], v230, s[14:15]
	s_waitcnt vmcnt(0)
	ds_write_b128 v229, v[236:239]
	ds_write_b128 v230, v[240:243]
	s_waitcnt lgkmcnt(0)
	s_barrier
